# sample-row attention units (160 keys) use a five-block instance of the hand-scheduled single-pass core
# baseline (speedup 1.0000x reference)
.LBB0_474:
	v_add_u32_e32 v1, 1, v2
	v_cvt_f32_i32_e32 v1, v1
	s_mov_b32 s0, 0xc2fc0000
	v_and_b32_e32 v68, 63, v65
	v_lshrrev_b32_e32 v70, 5, v68
	v_mul_f32_e32 v2, -0.5, v1
	v_cmp_gt_f32_e32 vcc, s0, v2
	v_mul_f32_e32 v164, 0x3fb8aa3b, v0
	s_cmpk_lg_i32 s3, 0xc0
	v_cndmask_b32_e32 v2, 0, v244, vcc
	v_fmac_f32_e32 v2, -0.5, v1
	v_exp_f32_e32 v1, v2
	v_cndmask_b32_e32 v2, 0, v245, vcc
	s_mov_b64 s[0:1], -1
	v_lshlrev_b32_e32 v69, 4, v70
	v_ldexp_f32 v1, v1, v2
	v_mul_f32_e32 v157, 0x3fb8aa3b, v1
	s_cbranch_scc0 .LBB0_500
	s_cmpk_eq_i32 s3, 0xa0
	s_cbranch_scc1 .Lswa5_core
	v_mad_u32_u24 v0, v66, s17, 0
	v_add_u32_e32 v72, v0, v69
	ds_read_b128 v[0:3], v72
	ds_read_b128 v[4:7], v72 offset:32
	s_cmpk_gt_u32 s3, 0x5f
	s_cselect_b64 s[10:11], -1, 0
	s_cmpk_lt_u32 s3, 0x60
	s_waitcnt lgkmcnt(1)
	v_mfma_f32_32x32x16_bf16 v[16:31], v[0:3], v[104:107], 0
	ds_read_b128 v[0:3], v72 offset:64
	ds_read_b128 v[32:35], v72 offset:4640
	s_waitcnt lgkmcnt(2)
	v_mfma_f32_32x32x16_bf16 v[16:31], v[4:7], v[108:111], v[16:31]
	s_waitcnt lgkmcnt(1)
	v_mfma_f32_32x32x16_bf16 v[16:31], v[0:3], v[112:115], v[16:31]
	ds_read_b128 v[0:3], v72 offset:96
	s_waitcnt lgkmcnt(0)
	v_mfma_f32_32x32x16_bf16 v[16:31], v[0:3], v[116:119], v[16:31]
	ds_read_b128 v[0:3], v72 offset:4608
	s_waitcnt lgkmcnt(0)
	v_mfma_f32_32x32x16_bf16 v[0:15], v[0:3], v[104:107], 0
	v_mfma_f32_32x32x16_bf16 v[0:15], v[32:35], v[108:111], v[0:15]
	ds_read_b128 v[32:35], v72 offset:4672
	s_waitcnt lgkmcnt(0)
	v_mfma_f32_32x32x16_bf16 v[0:15], v[32:35], v[112:115], v[0:15]
	ds_read_b128 v[32:35], v72 offset:4704
	s_waitcnt lgkmcnt(0)
	v_mfma_f32_32x32x16_bf16 v[0:15], v[32:35], v[116:119], v[0:15]
	v_mov_b32_e32 v32, 0
	v_mov_b32_e32 v33, v32
	v_mov_b32_e32 v34, v32
	v_mov_b32_e32 v35, v32
	v_mov_b32_e32 v36, v32
	v_mov_b32_e32 v37, v32
	v_mov_b32_e32 v38, v32
	v_mov_b32_e32 v39, v32
	v_mov_b32_e32 v40, v32
	v_mov_b32_e32 v41, v32
	v_mov_b32_e32 v42, v32
	v_mov_b32_e32 v43, v32
	v_mov_b32_e32 v44, v32
	v_mov_b32_e32 v45, v32
	v_mov_b32_e32 v46, v32
	v_mov_b32_e32 v47, v32
	s_cbranch_scc1 .LBB0_477
	ds_read_b128 v[32:35], v72 offset:9216
	ds_read_b128 v[48:51], v72 offset:9248
	s_waitcnt lgkmcnt(1)
	v_mfma_f32_32x32x16_bf16 v[32:47], v[32:35], v[104:107], 0
	s_waitcnt lgkmcnt(0)
	v_mfma_f32_32x32x16_bf16 v[32:47], v[48:51], v[108:111], v[32:47]
	ds_read_b128 v[48:51], v72 offset:9280
	s_waitcnt lgkmcnt(0)
	v_mfma_f32_32x32x16_bf16 v[32:47], v[48:51], v[112:115], v[32:47]
	ds_read_b128 v[48:51], v72 offset:9312
	s_waitcnt lgkmcnt(0)
	v_mfma_f32_32x32x16_bf16 v[32:47], v[48:51], v[116:119], v[32:47]

.Lswa5_core:
	v_lshlrev_b32_e32 v194, 2, v70
	v_or_b32_e32 v247, 0x80, v67
	v_sub_u32_e32 v247, v247, v194
	v_cvt_f32_u32_e32 v156, v247
	v_mul_f32_e32 v240, 0x40b17218, v157
	v_mul_u32_u24_e32 v252, 0x90, v66
	v_add_u32_e32 v192, v252, v69
	ds_read_b128 v[0:3], v192 offset:0
	ds_read_b128 v[4:7], v192 offset:32
	ds_read_b128 v[8:11], v192 offset:64
	ds_read_b128 v[12:15], v192 offset:96
	ds_read_b128 v[236:239], v192 offset:4608
	ds_read_b128 v[248:251], v192 offset:4640
	ds_read_b128 v[184:187], v192 offset:4672
	ds_read_b128 v[188:191], v192 offset:4704
	v_mul_f32_e64 v241, -v240, v156
	v_lshrrev_b32_e32 v247, 2, v65
	v_and_or_b32 v247, v247, 3, v194
	v_mul_u32_u24_e32 v202, 0xc0, v247
	v_lshlrev_b32_e32 v247, 1, v68
	v_and_b32_e32 v247, 32, v247
	v_lshlrev_b32_e32 v252, 3, v68
	v_and_b32_e32 v252, 24, v252
	v_add3_u32 v202, v202, v247, v252
	v_fmamk_f32 v32, v240, 0x00000000, v241
	v_fmamk_f32 v33, v240, 0x3f800000, v241
	v_fmamk_f32 v34, v240, 0x40000000, v241
	v_fmamk_f32 v35, v240, 0x40400000, v241
	v_fmamk_f32 v36, v240, 0x41000000, v241
	v_fmamk_f32 v37, v240, 0x41100000, v241
	v_fmamk_f32 v38, v240, 0x41200000, v241
	v_fmamk_f32 v39, v240, 0x41300000, v241
	v_fmamk_f32 v40, v240, 0x41800000, v241
	v_fmamk_f32 v41, v240, 0x41880000, v241
	v_fmamk_f32 v42, v240, 0x41900000, v241
	v_fmamk_f32 v43, v240, 0x41980000, v241
	v_fmamk_f32 v44, v240, 0x41c00000, v241
	v_fmamk_f32 v45, v240, 0x41c80000, v241
	v_fmamk_f32 v46, v240, 0x41d00000, v241
	v_fmamk_f32 v47, v240, 0x41d80000, v241
	s_waitcnt lgkmcnt(7)
	s_nop 0
	v_mfma_f32_32x32x16_bf16 v[32:47], v[0:3], v[104:107], v[32:47]
	v_fmamk_f32 v48, v240, 0x42000000, v241
	v_fmamk_f32 v49, v240, 0x42040000, v241
	v_fmamk_f32 v50, v240, 0x42080000, v241
	v_fmamk_f32 v51, v240, 0x420c0000, v241
	v_fmamk_f32 v52, v240, 0x42200000, v241
	s_waitcnt lgkmcnt(6)
	v_mfma_f32_32x32x16_bf16 v[32:47], v[4:7], v[108:111], v[32:47]
	v_fmamk_f32 v53, v240, 0x42240000, v241
	v_fmamk_f32 v54, v240, 0x42280000, v241
	v_fmamk_f32 v55, v240, 0x422c0000, v241
	v_fmamk_f32 v56, v240, 0x42400000, v241
	v_fmamk_f32 v57, v240, 0x42440000, v241
	s_waitcnt lgkmcnt(5)
	v_mfma_f32_32x32x16_bf16 v[32:47], v[8:11], v[112:115], v[32:47]
	v_fmamk_f32 v58, v240, 0x42480000, v241
	v_fmamk_f32 v59, v240, 0x424c0000, v241
	v_fmamk_f32 v60, v240, 0x42600000, v241
	v_fmamk_f32 v61, v240, 0x42640000, v241
	v_fmamk_f32 v62, v240, 0x42680000, v241
	s_waitcnt lgkmcnt(4)
	v_mfma_f32_32x32x16_bf16 v[32:47], v[12:15], v[116:119], v[32:47]
	v_fmamk_f32 v63, v240, 0x426c0000, v241
	ds_read_b128 v[0:3], v192 offset:9216
	ds_read_b128 v[4:7], v192 offset:9248
	ds_read_b128 v[8:11], v192 offset:9280
	ds_read_b128 v[12:15], v192 offset:9312
	s_waitcnt lgkmcnt(7)
	v_mfma_f32_32x32x16_bf16 v[48:63], v[236:239], v[104:107], v[48:63]
	v_fmamk_f32 v64, v240, 0x42800000, v241
	v_fmamk_f32 v65, v240, 0x42820000, v241
	v_fmamk_f32 v66, v240, 0x42840000, v241
	v_fmamk_f32 v67, v240, 0x42860000, v241
	v_fmamk_f32 v68, v240, 0x42900000, v241
	s_waitcnt lgkmcnt(6)
	v_mfma_f32_32x32x16_bf16 v[48:63], v[248:251], v[108:111], v[48:63]
	v_fmamk_f32 v69, v240, 0x42920000, v241
	v_fmamk_f32 v70, v240, 0x42940000, v241
	v_fmamk_f32 v71, v240, 0x42960000, v241
	v_fmamk_f32 v72, v240, 0x42a00000, v241
	v_fmamk_f32 v73, v240, 0x42a20000, v241
	s_waitcnt lgkmcnt(5)
	v_mfma_f32_32x32x16_bf16 v[48:63], v[184:187], v[112:115], v[48:63]
	v_fmamk_f32 v74, v240, 0x42a40000, v241
	v_fmamk_f32 v75, v240, 0x42a60000, v241
	v_fmamk_f32 v76, v240, 0x42b00000, v241
	v_fmamk_f32 v77, v240, 0x42b20000, v241
	v_fmamk_f32 v78, v240, 0x42b40000, v241
	s_waitcnt lgkmcnt(4)
	v_mfma_f32_32x32x16_bf16 v[48:63], v[188:191], v[116:119], v[48:63]
	v_fmamk_f32 v79, v240, 0x42b60000, v241
	ds_read_b128 v[236:239], v192 offset:13824
	ds_read_b128 v[248:251], v192 offset:13856
	ds_read_b128 v[184:187], v192 offset:13888
	ds_read_b128 v[188:191], v192 offset:13920
	s_waitcnt lgkmcnt(7)
	v_mfma_f32_32x32x16_bf16 v[64:79], v[0:3], v[104:107], v[64:79]
	v_fmamk_f32 v168, v240, 0x42c00000, v241
	v_fmamk_f32 v169, v240, 0x42c20000, v241
	v_fmamk_f32 v170, v240, 0x42c40000, v241
	v_fmamk_f32 v171, v240, 0x42c60000, v241
	v_fmamk_f32 v172, v240, 0x42d00000, v241
	s_waitcnt lgkmcnt(6)
	v_mfma_f32_32x32x16_bf16 v[64:79], v[4:7], v[108:111], v[64:79]
	v_fmamk_f32 v173, v240, 0x42d20000, v241
	v_fmamk_f32 v174, v240, 0x42d40000, v241
	v_fmamk_f32 v175, v240, 0x42d60000, v241
	v_fmamk_f32 v176, v240, 0x42e00000, v241
	v_fmamk_f32 v177, v240, 0x42e20000, v241
	s_waitcnt lgkmcnt(5)
	v_mfma_f32_32x32x16_bf16 v[64:79], v[8:11], v[112:115], v[64:79]
	v_fmamk_f32 v178, v240, 0x42e40000, v241
	v_fmamk_f32 v179, v240, 0x42e60000, v241
	v_fmamk_f32 v180, v240, 0x42f00000, v241
	v_fmamk_f32 v181, v240, 0x42f20000, v241
	v_fmamk_f32 v182, v240, 0x42f40000, v241
	s_waitcnt lgkmcnt(4)
	v_mfma_f32_32x32x16_bf16 v[64:79], v[12:15], v[116:119], v[64:79]
	v_fmamk_f32 v183, v240, 0x42f60000, v241
	ds_read_b128 v[0:3], v192 offset:18432
	ds_read_b128 v[4:7], v192 offset:18464
	ds_read_b128 v[8:11], v192 offset:18496
	ds_read_b128 v[12:15], v192 offset:18528
	s_waitcnt lgkmcnt(7)
	v_mfma_f32_32x32x16_bf16 v[168:183], v[236:239], v[104:107], v[168:183]
	v_subrev_f32_e32 v220, 0x43000000, v156
	v_mul_f32_e64 v220, -|v220|, v240
	v_subrev_f32_e32 v221, 0x43010000, v156
	v_mul_f32_e64 v221, -|v221|, v240
	v_subrev_f32_e32 v222, 0x43020000, v156
	v_mul_f32_e64 v222, -|v222|, v240
	v_subrev_f32_e32 v223, 0x43030000, v156
	v_mul_f32_e64 v223, -|v223|, v240
	s_waitcnt lgkmcnt(6)
	v_mfma_f32_32x32x16_bf16 v[168:183], v[248:251], v[108:111], v[168:183]
	v_subrev_f32_e32 v224, 0x43080000, v156
	v_mul_f32_e64 v224, -|v224|, v240
	v_subrev_f32_e32 v225, 0x43090000, v156
	v_mul_f32_e64 v225, -|v225|, v240
	v_subrev_f32_e32 v226, 0x430a0000, v156
	v_mul_f32_e64 v226, -|v226|, v240
	v_subrev_f32_e32 v227, 0x430b0000, v156
	v_mul_f32_e64 v227, -|v227|, v240
	s_waitcnt lgkmcnt(5)
	v_mfma_f32_32x32x16_bf16 v[168:183], v[184:187], v[112:115], v[168:183]
	v_subrev_f32_e32 v228, 0x43100000, v156
	v_mul_f32_e64 v228, -|v228|, v240
	v_subrev_f32_e32 v229, 0x43110000, v156
	v_mul_f32_e64 v229, -|v229|, v240
	v_subrev_f32_e32 v230, 0x43120000, v156
	v_mul_f32_e64 v230, -|v230|, v240
	v_subrev_f32_e32 v231, 0x43130000, v156
	v_mul_f32_e64 v231, -|v231|, v240
	s_waitcnt lgkmcnt(4)
	v_mfma_f32_32x32x16_bf16 v[168:183], v[188:191], v[116:119], v[168:183]
	v_subrev_f32_e32 v232, 0x43180000, v156
	v_mul_f32_e64 v232, -|v232|, v240
	v_subrev_f32_e32 v233, 0x43190000, v156
	v_mul_f32_e64 v233, -|v233|, v240
	v_subrev_f32_e32 v234, 0x431a0000, v156
	v_mul_f32_e64 v234, -|v234|, v240
	v_subrev_f32_e32 v235, 0x431b0000, v156
	v_mul_f32_e64 v235, -|v235|, v240
	s_waitcnt lgkmcnt(3)
	s_nop 0
	v_mfma_f32_32x32x16_bf16 v[220:235], v[0:3], v[104:107], v[220:235]
	s_waitcnt lgkmcnt(2)
	v_mfma_f32_32x32x16_bf16 v[220:235], v[4:7], v[108:111], v[220:235]
	s_waitcnt lgkmcnt(1)
	v_mfma_f32_32x32x16_bf16 v[220:235], v[8:11], v[112:115], v[220:235]
	s_waitcnt lgkmcnt(0)
	v_mfma_f32_32x32x16_bf16 v[220:235], v[12:15], v[116:119], v[220:235]
	v_max_f32_e32 v218, v32, v33
	v_max_f32_e32 v219, v34, v35
	v_max_f32_e32 v246, v36, v37
	v_max3_f32 v218, v218, v38, v39
	v_max3_f32 v219, v219, v40, v41
	v_max3_f32 v246, v246, v42, v43
	v_max3_f32 v218, v218, v44, v45
	v_max3_f32 v219, v219, v46, v47
	v_max3_f32 v246, v246, v48, v49
	v_max3_f32 v218, v218, v50, v51
	v_max3_f32 v219, v219, v52, v53
	v_max3_f32 v246, v246, v54, v55
	v_max3_f32 v218, v218, v56, v57
	v_max3_f32 v219, v219, v58, v59
	v_max3_f32 v246, v246, v60, v61
	v_max3_f32 v218, v218, v62, v63
	v_max3_f32 v219, v219, v64, v65
	v_max3_f32 v246, v246, v66, v67
	v_max3_f32 v218, v218, v68, v69
	v_max3_f32 v219, v219, v70, v71
	v_max3_f32 v246, v246, v72, v73
	v_max3_f32 v218, v218, v74, v75
	v_max3_f32 v219, v219, v76, v77
	v_max3_f32 v246, v246, v78, v79
	v_max3_f32 v218, v218, v168, v169
	v_max3_f32 v219, v219, v170, v171
	v_max3_f32 v246, v246, v172, v173
	v_max3_f32 v218, v218, v174, v175
	v_max3_f32 v219, v219, v176, v177
	v_max3_f32 v246, v246, v178, v179
	v_max3_f32 v218, v218, v180, v181
	v_max3_f32 v219, v219, v182, v183
	v_max3_f32 v246, v246, v220, v221
	v_max3_f32 v218, v218, v222, v223
	v_max3_f32 v219, v219, v224, v225
	v_max3_f32 v246, v246, v226, v227
	v_max3_f32 v218, v218, v228, v229
	v_max3_f32 v219, v219, v230, v231
	v_max3_f32 v246, v246, v232, v233
	v_max3_f32 v218, v218, v234, v235
	v_max3_f32 v218, v218, v219, v246
	v_mov_b32_e32 v219, v218
	s_nop 1
	v_permlane32_swap_b32_e32 v218, v219
	v_max_f32_e32 v218, v218, v219
	v_mul_f32_e32 v218, v204, v218
	v_max_f32_e32 v218, v218, v164
	ds_read_b64_tr_b16 v[236:237], v202 offset:27648
	ds_read_b64_tr_b16 v[238:239], v202 offset:29184
	ds_read_b64_tr_b16 v[248:249], v202 offset:27712
	ds_read_b64_tr_b16 v[250:251], v202 offset:29248
	v_fma_f32 v32, v32, v204, -v218
	v_fma_f32 v33, v33, v204, -v218
	v_fma_f32 v34, v34, v204, -v218
	v_fma_f32 v35, v35, v204, -v218
	v_fma_f32 v36, v36, v204, -v218
	v_fma_f32 v37, v37, v204, -v218
	v_fma_f32 v38, v38, v204, -v218
	v_fma_f32 v39, v39, v204, -v218
	v_exp_f32_e32 v32, v32
	v_exp_f32_e32 v33, v33
	v_exp_f32_e32 v34, v34
	v_exp_f32_e32 v35, v35
	v_exp_f32_e32 v36, v36
	v_exp_f32_e32 v37, v37
	v_exp_f32_e32 v38, v38
	v_exp_f32_e32 v39, v39
	v_mov_b32_e32 v165, v32
	v_mov_b32_e32 v166, v33
	v_mov_b32_e32 v167, v34
	v_mov_b32_e32 v134, v35
	v_add_f32_e32 v165, v165, v36
	v_add_f32_e32 v166, v166, v37
	v_add_f32_e32 v167, v167, v38
	v_add_f32_e32 v134, v134, v39
	v_cvt_pk_bf16_f32 v32, v32, v33
	v_cvt_pk_bf16_f32 v33, v34, v35
	v_cvt_pk_bf16_f32 v34, v36, v37
	v_cvt_pk_bf16_f32 v35, v38, v39
	v_fma_f32 v40, v40, v204, -v218
	v_fma_f32 v41, v41, v204, -v218
	v_fma_f32 v42, v42, v204, -v218
	v_fma_f32 v43, v43, v204, -v218
	v_fma_f32 v44, v44, v204, -v218
	v_fma_f32 v45, v45, v204, -v218
	v_fma_f32 v46, v46, v204, -v218
	v_fma_f32 v47, v47, v204, -v218
	v_exp_f32_e32 v40, v40
	v_exp_f32_e32 v41, v41
	v_exp_f32_e32 v42, v42
	v_exp_f32_e32 v43, v43
	v_exp_f32_e32 v44, v44
	v_exp_f32_e32 v45, v45
	v_exp_f32_e32 v46, v46
	v_exp_f32_e32 v47, v47
	v_add_f32_e32 v165, v165, v40
	v_add_f32_e32 v166, v166, v41
	v_add_f32_e32 v167, v167, v42
	v_add_f32_e32 v134, v134, v43
	v_add_f32_e32 v165, v165, v44
	v_add_f32_e32 v166, v166, v45
	v_add_f32_e32 v167, v167, v46
	v_add_f32_e32 v134, v134, v47
	v_cvt_pk_bf16_f32 v36, v40, v41
	v_cvt_pk_bf16_f32 v37, v42, v43
	v_cvt_pk_bf16_f32 v38, v44, v45
	v_cvt_pk_bf16_f32 v39, v46, v47
	ds_read_b64_tr_b16 v[40:41], v202 offset:30720
	ds_read_b64_tr_b16 v[42:43], v202 offset:32256
	ds_read_b64_tr_b16 v[44:45], v202 offset:30784
	ds_read_b64_tr_b16 v[46:47], v202 offset:32320
	s_waitcnt lgkmcnt(6)
	v_mfma_f32_32x32x16_bf16 v[0:15], v[236:239], v[32:35], 0
	v_fma_f32 v48, v48, v204, -v218
	v_fma_f32 v49, v49, v204, -v218
	v_fma_f32 v50, v50, v204, -v218
	v_fma_f32 v51, v51, v204, -v218
	v_fma_f32 v52, v52, v204, -v218
	v_fma_f32 v53, v53, v204, -v218
	v_fma_f32 v54, v54, v204, -v218
	v_fma_f32 v55, v55, v204, -v218
	v_exp_f32_e32 v48, v48
	v_exp_f32_e32 v49, v49
	v_exp_f32_e32 v50, v50
	v_exp_f32_e32 v51, v51
	v_exp_f32_e32 v52, v52
	v_exp_f32_e32 v53, v53
	s_waitcnt lgkmcnt(4)
	v_mfma_f32_32x32x16_bf16 v[16:31], v[248:251], v[32:35], 0
	v_exp_f32_e32 v54, v54
	v_exp_f32_e32 v55, v55
	v_add_f32_e32 v165, v165, v48
	v_add_f32_e32 v166, v166, v49
	v_add_f32_e32 v167, v167, v50
	v_add_f32_e32 v134, v134, v51
	v_add_f32_e32 v165, v165, v52
	v_add_f32_e32 v166, v166, v53
	v_add_f32_e32 v167, v167, v54
	v_add_f32_e32 v134, v134, v55
	v_cvt_pk_bf16_f32 v48, v48, v49
	v_cvt_pk_bf16_f32 v49, v50, v51
	v_cvt_pk_bf16_f32 v50, v52, v53
	v_cvt_pk_bf16_f32 v51, v54, v55
	ds_read_b64_tr_b16 v[236:237], v202 offset:33792
	ds_read_b64_tr_b16 v[238:239], v202 offset:35328
	ds_read_b64_tr_b16 v[248:249], v202 offset:33856
	ds_read_b64_tr_b16 v[250:251], v202 offset:35392
	s_waitcnt lgkmcnt(6)
	v_mfma_f32_32x32x16_bf16 v[0:15], v[40:43], v[36:39], v[0:15]
	v_fma_f32 v56, v56, v204, -v218
	v_fma_f32 v57, v57, v204, -v218
	v_fma_f32 v58, v58, v204, -v218
	v_fma_f32 v59, v59, v204, -v218
	v_fma_f32 v60, v60, v204, -v218
	v_fma_f32 v61, v61, v204, -v218
	v_fma_f32 v62, v62, v204, -v218
	v_fma_f32 v63, v63, v204, -v218
	v_exp_f32_e32 v56, v56
	v_exp_f32_e32 v57, v57
	v_exp_f32_e32 v58, v58
	v_exp_f32_e32 v59, v59
	v_exp_f32_e32 v60, v60
	v_exp_f32_e32 v61, v61
	s_waitcnt lgkmcnt(4)
	v_mfma_f32_32x32x16_bf16 v[16:31], v[44:47], v[36:39], v[16:31]
	v_exp_f32_e32 v62, v62
	v_exp_f32_e32 v63, v63
	v_add_f32_e32 v165, v165, v56
	v_add_f32_e32 v166, v166, v57
	v_add_f32_e32 v167, v167, v58
	v_add_f32_e32 v134, v134, v59
	v_add_f32_e32 v165, v165, v60
	v_add_f32_e32 v166, v166, v61
	v_add_f32_e32 v167, v167, v62
	v_add_f32_e32 v134, v134, v63
	v_cvt_pk_bf16_f32 v52, v56, v57
	v_cvt_pk_bf16_f32 v53, v58, v59
	v_cvt_pk_bf16_f32 v54, v60, v61
	v_cvt_pk_bf16_f32 v55, v62, v63
	ds_read_b64_tr_b16 v[40:41], v202 offset:36864
	ds_read_b64_tr_b16 v[42:43], v202 offset:38400
	ds_read_b64_tr_b16 v[44:45], v202 offset:36928
	ds_read_b64_tr_b16 v[46:47], v202 offset:38464
	ds_read_b64_tr_b16 v[56:57], v202 offset:39936
	ds_read_b64_tr_b16 v[58:59], v202 offset:41472
	ds_read_b64_tr_b16 v[60:61], v202 offset:40000
	ds_read_b64_tr_b16 v[62:63], v202 offset:41536
	s_waitcnt lgkmcnt(10)
	v_mfma_f32_32x32x16_bf16 v[0:15], v[236:239], v[48:51], v[0:15]
	v_fma_f32 v64, v64, v204, -v218
	v_fma_f32 v65, v65, v204, -v218
	v_fma_f32 v66, v66, v204, -v218
	v_fma_f32 v67, v67, v204, -v218
	v_fma_f32 v68, v68, v204, -v218
	v_fma_f32 v69, v69, v204, -v218
	v_fma_f32 v70, v70, v204, -v218
	v_fma_f32 v71, v71, v204, -v218
	v_exp_f32_e32 v64, v64
	v_exp_f32_e32 v65, v65
	v_exp_f32_e32 v66, v66
	v_exp_f32_e32 v67, v67
	v_exp_f32_e32 v68, v68
	v_exp_f32_e32 v69, v69
	s_waitcnt lgkmcnt(8)
	v_mfma_f32_32x32x16_bf16 v[16:31], v[248:251], v[48:51], v[16:31]
	v_exp_f32_e32 v70, v70
	v_exp_f32_e32 v71, v71
	v_add_f32_e32 v165, v165, v64
	v_add_f32_e32 v166, v166, v65
	v_add_f32_e32 v167, v167, v66
	v_add_f32_e32 v134, v134, v67
	v_add_f32_e32 v165, v165, v68
	v_add_f32_e32 v166, v166, v69
	v_add_f32_e32 v167, v167, v70
	v_add_f32_e32 v134, v134, v71
	v_cvt_pk_bf16_f32 v64, v64, v65
	v_cvt_pk_bf16_f32 v65, v66, v67
	v_cvt_pk_bf16_f32 v66, v68, v69
	v_cvt_pk_bf16_f32 v67, v70, v71
	ds_read_b64_tr_b16 v[236:237], v202 offset:43008
	ds_read_b64_tr_b16 v[238:239], v202 offset:44544
	ds_read_b64_tr_b16 v[248:249], v202 offset:43072
	ds_read_b64_tr_b16 v[250:251], v202 offset:44608
	s_waitcnt lgkmcnt(10)
	v_mfma_f32_32x32x16_bf16 v[0:15], v[40:43], v[52:55], v[0:15]
	v_fma_f32 v72, v72, v204, -v218
	v_fma_f32 v73, v73, v204, -v218
	v_fma_f32 v74, v74, v204, -v218
	v_fma_f32 v75, v75, v204, -v218
	v_fma_f32 v76, v76, v204, -v218
	v_fma_f32 v77, v77, v204, -v218
	v_fma_f32 v78, v78, v204, -v218
	v_fma_f32 v79, v79, v204, -v218
	v_exp_f32_e32 v72, v72
	v_exp_f32_e32 v73, v73
	v_exp_f32_e32 v74, v74
	v_exp_f32_e32 v75, v75
	v_exp_f32_e32 v76, v76
	v_exp_f32_e32 v77, v77
	s_waitcnt lgkmcnt(8)
	v_mfma_f32_32x32x16_bf16 v[16:31], v[44:47], v[52:55], v[16:31]
	v_exp_f32_e32 v78, v78
	v_exp_f32_e32 v79, v79
	v_add_f32_e32 v165, v165, v72
	v_add_f32_e32 v166, v166, v73
	v_add_f32_e32 v167, v167, v74
	v_add_f32_e32 v134, v134, v75
	v_add_f32_e32 v165, v165, v76
	v_add_f32_e32 v166, v166, v77
	v_add_f32_e32 v167, v167, v78
	v_add_f32_e32 v134, v134, v79
	v_cvt_pk_bf16_f32 v68, v72, v73
	v_cvt_pk_bf16_f32 v69, v74, v75
	v_cvt_pk_bf16_f32 v70, v76, v77
	v_cvt_pk_bf16_f32 v71, v78, v79
	ds_read_b64_tr_b16 v[40:41], v202 offset:46080
	ds_read_b64_tr_b16 v[42:43], v202 offset:47616
	ds_read_b64_tr_b16 v[44:45], v202 offset:46144
	ds_read_b64_tr_b16 v[46:47], v202 offset:47680
	s_waitcnt lgkmcnt(10)
	v_mfma_f32_32x32x16_bf16 v[0:15], v[56:59], v[64:67], v[0:15]
	v_fma_f32 v168, v168, v204, -v218
	v_fma_f32 v169, v169, v204, -v218
	v_fma_f32 v170, v170, v204, -v218
	v_fma_f32 v171, v171, v204, -v218
	v_fma_f32 v172, v172, v204, -v218
	v_fma_f32 v173, v173, v204, -v218
	v_fma_f32 v174, v174, v204, -v218
	v_fma_f32 v175, v175, v204, -v218
	v_exp_f32_e32 v168, v168
	v_exp_f32_e32 v169, v169
	v_exp_f32_e32 v170, v170
	v_exp_f32_e32 v171, v171
	v_exp_f32_e32 v172, v172
	v_exp_f32_e32 v173, v173
	s_waitcnt lgkmcnt(8)
	v_mfma_f32_32x32x16_bf16 v[16:31], v[60:63], v[64:67], v[16:31]
	v_exp_f32_e32 v174, v174
	v_exp_f32_e32 v175, v175
	v_add_f32_e32 v165, v165, v168
	v_add_f32_e32 v166, v166, v169
	v_add_f32_e32 v167, v167, v170
	v_add_f32_e32 v134, v134, v171
	v_add_f32_e32 v165, v165, v172
	v_add_f32_e32 v166, v166, v173
	v_add_f32_e32 v167, v167, v174
	v_add_f32_e32 v134, v134, v175
	v_cvt_pk_bf16_f32 v168, v168, v169
	v_cvt_pk_bf16_f32 v169, v170, v171
	v_cvt_pk_bf16_f32 v170, v172, v173
	v_cvt_pk_bf16_f32 v171, v174, v175
	ds_read_b64_tr_b16 v[56:57], v202 offset:49152
	ds_read_b64_tr_b16 v[58:59], v202 offset:50688
	ds_read_b64_tr_b16 v[60:61], v202 offset:49216
	ds_read_b64_tr_b16 v[62:63], v202 offset:50752
	s_waitcnt lgkmcnt(10)
	v_mfma_f32_32x32x16_bf16 v[0:15], v[236:239], v[68:71], v[0:15]
	v_fma_f32 v176, v176, v204, -v218
	v_fma_f32 v177, v177, v204, -v218
	v_fma_f32 v178, v178, v204, -v218
	v_fma_f32 v179, v179, v204, -v218
	v_fma_f32 v180, v180, v204, -v218
	v_fma_f32 v181, v181, v204, -v218
	v_fma_f32 v182, v182, v204, -v218
	v_fma_f32 v183, v183, v204, -v218
	v_exp_f32_e32 v176, v176
	v_exp_f32_e32 v177, v177
	v_exp_f32_e32 v178, v178
	v_exp_f32_e32 v179, v179
	v_exp_f32_e32 v180, v180
	v_exp_f32_e32 v181, v181
	s_waitcnt lgkmcnt(8)
	v_mfma_f32_32x32x16_bf16 v[16:31], v[248:251], v[68:71], v[16:31]
	v_exp_f32_e32 v182, v182
	v_exp_f32_e32 v183, v183
	v_add_f32_e32 v165, v165, v176
	v_add_f32_e32 v166, v166, v177
	v_add_f32_e32 v167, v167, v178
	v_add_f32_e32 v134, v134, v179
	v_add_f32_e32 v165, v165, v180
	v_add_f32_e32 v166, v166, v181
	v_add_f32_e32 v167, v167, v182
	v_add_f32_e32 v134, v134, v183
	v_cvt_pk_bf16_f32 v172, v176, v177
	v_cvt_pk_bf16_f32 v173, v178, v179
	v_cvt_pk_bf16_f32 v174, v180, v181
	v_cvt_pk_bf16_f32 v175, v182, v183
	ds_read_b64_tr_b16 v[236:237], v202 offset:52224
	ds_read_b64_tr_b16 v[238:239], v202 offset:53760
	ds_read_b64_tr_b16 v[248:249], v202 offset:52288
	ds_read_b64_tr_b16 v[250:251], v202 offset:53824
	s_waitcnt lgkmcnt(10)
	v_mfma_f32_32x32x16_bf16 v[0:15], v[40:43], v[168:171], v[0:15]
	v_fma_f32 v220, v220, v204, -v218
	v_fma_f32 v221, v221, v204, -v218
	v_fma_f32 v222, v222, v204, -v218
	v_fma_f32 v223, v223, v204, -v218
	v_fma_f32 v224, v224, v204, -v218
	v_fma_f32 v225, v225, v204, -v218
	v_fma_f32 v226, v226, v204, -v218
	v_fma_f32 v227, v227, v204, -v218
	v_exp_f32_e32 v220, v220
	v_exp_f32_e32 v221, v221
	v_exp_f32_e32 v222, v222
	v_exp_f32_e32 v223, v223
	v_exp_f32_e32 v224, v224
	v_exp_f32_e32 v225, v225
	s_waitcnt lgkmcnt(8)
	v_mfma_f32_32x32x16_bf16 v[16:31], v[44:47], v[168:171], v[16:31]
	v_exp_f32_e32 v226, v226
	v_exp_f32_e32 v227, v227
	v_add_f32_e32 v165, v165, v220
	v_add_f32_e32 v166, v166, v221
	v_add_f32_e32 v167, v167, v222
	v_add_f32_e32 v134, v134, v223
	v_add_f32_e32 v165, v165, v224
	v_add_f32_e32 v166, v166, v225
	v_add_f32_e32 v167, v167, v226
	v_add_f32_e32 v134, v134, v227
	v_cvt_pk_bf16_f32 v220, v220, v221
	v_cvt_pk_bf16_f32 v221, v222, v223
	v_cvt_pk_bf16_f32 v222, v224, v225
	v_cvt_pk_bf16_f32 v223, v226, v227
	ds_read_b64_tr_b16 v[40:41], v202 offset:55296
	ds_read_b64_tr_b16 v[42:43], v202 offset:56832
	ds_read_b64_tr_b16 v[44:45], v202 offset:55360
	ds_read_b64_tr_b16 v[46:47], v202 offset:56896
	s_waitcnt lgkmcnt(10)
	v_mfma_f32_32x32x16_bf16 v[0:15], v[56:59], v[172:175], v[0:15]
	v_fma_f32 v228, v228, v204, -v218
	v_fma_f32 v229, v229, v204, -v218
	v_fma_f32 v230, v230, v204, -v218
	v_fma_f32 v231, v231, v204, -v218
	v_fma_f32 v232, v232, v204, -v218
	v_fma_f32 v233, v233, v204, -v218
	v_fma_f32 v234, v234, v204, -v218
	v_fma_f32 v235, v235, v204, -v218
	v_exp_f32_e32 v228, v228
	v_exp_f32_e32 v229, v229
	v_exp_f32_e32 v230, v230
	v_exp_f32_e32 v231, v231
	v_exp_f32_e32 v232, v232
	v_exp_f32_e32 v233, v233
	s_waitcnt lgkmcnt(8)
	v_mfma_f32_32x32x16_bf16 v[16:31], v[60:63], v[172:175], v[16:31]
	v_exp_f32_e32 v234, v234
	v_exp_f32_e32 v235, v235
	v_add_f32_e32 v165, v165, v228
	v_add_f32_e32 v166, v166, v229
	v_add_f32_e32 v167, v167, v230
	v_add_f32_e32 v134, v134, v231
	v_add_f32_e32 v165, v165, v232
	v_add_f32_e32 v166, v166, v233
	v_add_f32_e32 v167, v167, v234
	v_add_f32_e32 v134, v134, v235
	v_cvt_pk_bf16_f32 v224, v228, v229
	v_cvt_pk_bf16_f32 v225, v230, v231
	v_cvt_pk_bf16_f32 v226, v232, v233
	v_cvt_pk_bf16_f32 v227, v234, v235
	s_waitcnt lgkmcnt(6)
	v_mfma_f32_32x32x16_bf16 v[0:15], v[236:239], v[220:223], v[0:15]
	s_waitcnt lgkmcnt(4)
	v_mfma_f32_32x32x16_bf16 v[16:31], v[248:251], v[220:223], v[16:31]
	s_waitcnt lgkmcnt(2)
	v_mfma_f32_32x32x16_bf16 v[0:15], v[40:43], v[224:227], v[0:15]
	s_waitcnt lgkmcnt(0)
	v_mfma_f32_32x32x16_bf16 v[16:31], v[44:47], v[224:227], v[16:31]
	v_add_f32_e32 v165, v165, v166
	v_add_f32_e32 v167, v167, v134
	v_xor_b32_e32 v205, 32, v197
	v_lshlrev_b32_e32 v205, 2, v205
	v_mov_b32_e32 v72, v218
	v_add_f32_e32 v74, v165, v167
	ds_bpermute_b32 v32, v205, v74
	s_branch .LBB0_431
